# attention loops made shorter in instruction count: diff-attention kt loop hand-rewritten (second half software-pipelined, one LDS wait per PV k-step, compact tile-class scalar logic, stage loads throu
# speedup vs baseline: 1.0244x; 1.0244x over previous
; DI void attn_diff_unit(const Params& p, int li, int b, int h, int qb, char* smem, bool pre, int nh, bool has_next) {
;     ...
;   f32x16 O[4];
; #pragma unroll
;   for (int j = 0; j < 4; ++j)
; #pragma unroll
;     for (int i = 0; i < 16; ++i) O[j][i] = 0.f;
;   float m = 0.f, l = 0.f;
;   const int krow = tid >> 4, kpart = tid & 15;
;   const u16* gk = kd + (size_t)(b * S_ + krow) * 1024 + h * 128 + kpart * 8;
;   const u16* gv = vT + (size_t)(b * S_ + krow) * 1024 + h * 128 + kpart * 8;
;   u32x4 rk[4], rv[4];
;   if (!pre) {
; #pragma unroll
;     for (int i = 0; i < 4; ++i) { rk[i] = *(const u32x4*)(gk + (size_t)i * 32 * 1024); rv[i] = *(const u32x4*)(gv + (size_t)i * 32 * 1024); }
;   }
;   auto put_stage = [&](char* kb) {
;     char* vb = kb + 128 * KR;
; #pragma unroll
;     for (int i = 0; i < 4; ++i) {
;       *(u32x4*)(kb + (krow + 32 * i) * KR + kpart * 16) = rk[i];
;       *(u32x4*)(vb + (krow + 32 * i) * VR + kpart * 16) = rv[i];
;     }
;   };
;   auto get_stage = [&](int st) {
;     const int k0 = st * 128;
; #pragma unroll
;     for (int i = 0; i < 4; ++i) { rk[i] = *(const u32x4*)(gk + (size_t)(k0 + i * 32) * 1024); rv[i] = *(const u32x4*)(gv + (size_t)(k0 + i * 32) * 1024); }
;   };
;   if (!pre) put_stage(smem);
;   __syncthreads();
;   get_stage(1);
.LBB0_567:
	v_bfe_u32 v4, v146, 2, 2
	v_lshrrev_b32_e32 v5, 3, v146
	v_and_or_b32 v4, v5, 4, v4
	s_mov_b32 s3, 0x40000
	v_mul_u32_u24_e32 v163, 0x140, v4
	v_add_co_u32_e32 v4, vcc, s3, v148
	s_waitcnt lgkmcnt(0)
	s_nop 0
	v_addc_co_u32_e32 v5, vcc, 0, v149, vcc
	v_add_co_u32_e32 v6, vcc, s3, v150
	s_mov_b32 s3, 0x50000
	s_nop 0
	v_addc_co_u32_e32 v7, vcc, 0, v151, vcc
	s_barrier
	global_load_dwordx4 v[116:119], v[4:5], off
	global_load_dwordx4 v[128:131], v[6:7], off
	v_add_co_u32_e32 v4, vcc, s3, v148
	s_and_b32 s35, s39, 0xf80
	s_nop 0
	v_addc_co_u32_e32 v5, vcc, 0, v149, vcc
	v_add_co_u32_e32 v6, vcc, s3, v150
	s_mov_b32 s3, 0x60000
	s_nop 0
	v_addc_co_u32_e32 v7, vcc, 0, v151, vcc
	global_load_dwordx4 v[112:115], v[4:5], off
	global_load_dwordx4 v[120:123], v[6:7], off
	v_add_co_u32_e32 v4, vcc, s3, v148
	s_add_i32 s40, s40, s89
	s_nop 0
	v_addc_co_u32_e32 v5, vcc, 0, v149, vcc
	v_add_co_u32_e32 v6, vcc, s3, v150
	s_mov_b32 s3, 0x70000
	s_nop 0
	v_addc_co_u32_e32 v7, vcc, 0, v151, vcc
	global_load_dwordx4 v[124:127], v[4:5], off
	global_load_dwordx4 v[132:135], v[6:7], off
	v_add_co_u32_e32 v4, vcc, s3, v148
	s_sub_i32 s42, 0, s35
	s_nop 0
	v_addc_co_u32_e32 v5, vcc, 0, v149, vcc
	v_add_co_u32_e32 v6, vcc, s3, v150
	s_lshr_b32 s2, s40, 5
	s_nop 0
	v_addc_co_u32_e32 v7, vcc, 0, v151, vcc
	global_load_dwordx4 v[136:139], v[4:5], off
	global_load_dwordx4 v[140:143], v[6:7], off
	v_and_b32_e32 v158, 63, v146
	s_cmpk_lt_u32 s40, 0x100
	v_lshlrev_b32_e32 v144, 10, v3
	s_cselect_b64 s[28:29], -1, 0
	s_cmpk_gt_u32 s40, 0xff
	v_and_b32_e32 v3, 16, v146
	v_lshlrev_b32_e32 v162, 2, v158
	s_cselect_b64 s[22:23], -1, 0
	v_and_or_b32 v3, v162, 12, v3
	s_sub_i32 s2, s2, s34
	v_lshlrev_b32_e32 v164, 1, v3
	v_lshlrev_b32_e32 v3, 7, v155
	v_add_u32_e32 v166, 0, v160
	s_lshl_b32 s2, s2, 7
	v_or_b32_e32 v1, s35, v1
	v_lshl_or_b32 v165, v2, 4, v3
	v_lshlrev_b32_e32 v153, 2, v2
	v_add_u32_e32 v2, 0, v161
	v_add_u32_e32 v3, 0x8800, v166
	s_ashr_i32 s3, s2, 31
	v_mul_u32_u24_e32 v167, 0x110, v0
	v_add_u32_e32 v0, v1, v0
	v_mov_b32_e32 v169, 0
	s_mov_b32 s24, 0
	v_xor_b32_e32 v147, 0x80, v162
	v_sub_u32_e32 v168, v153, v0
	s_mov_b64 s[34:35], 0xb0000
	v_add_u32_e32 v170, v2, v159
	v_add_u32_e32 v171, v3, v159
	s_lshl_b64 s[36:37], s[2:3], 1
	s_mov_b32 s43, 0
	v_mov_b32_e32 v172, 0
	v_mov_b32_e32 v0, 0
	v_mov_b32_e32 v1, v169
	v_mov_b32_e32 v2, v169
	v_mov_b32_e32 v3, v169
	v_mov_b32_e32 v4, v169
	v_mov_b32_e32 v5, v169
	v_mov_b32_e32 v6, v169
	v_mov_b32_e32 v7, v169
	v_mov_b32_e32 v8, v169
	v_mov_b32_e32 v9, v169
	v_mov_b32_e32 v10, v169
	v_mov_b32_e32 v11, v169
	v_mov_b32_e32 v12, v169
	v_mov_b32_e32 v13, v169
	v_mov_b32_e32 v14, v169
	v_mov_b32_e32 v15, v169
	v_mov_b32_e32 v16, 0
	v_mov_b32_e32 v17, v169
	v_mov_b32_e32 v18, v169
	v_mov_b32_e32 v19, v169
	v_mov_b32_e32 v20, v169
	v_mov_b32_e32 v21, v169
	v_mov_b32_e32 v22, v169
	v_mov_b32_e32 v23, v169
	v_mov_b32_e32 v24, v169
	v_mov_b32_e32 v25, v169
	v_mov_b32_e32 v26, v169
	v_mov_b32_e32 v27, v169
	v_mov_b32_e32 v28, v169
	v_mov_b32_e32 v29, v169
	v_mov_b32_e32 v30, v169
	v_mov_b32_e32 v31, v169
	v_mov_b32_e32 v32, 0
	v_mov_b32_e32 v33, v169
	v_mov_b32_e32 v34, v169
	v_mov_b32_e32 v35, v169
	v_mov_b32_e32 v36, v169
	v_mov_b32_e32 v37, v169
	v_mov_b32_e32 v38, v169
	v_mov_b32_e32 v39, v169
	v_mov_b32_e32 v40, v169
	v_mov_b32_e32 v41, v169
	v_mov_b32_e32 v42, v169
	v_mov_b32_e32 v43, v169
	v_mov_b32_e32 v44, v169
	v_mov_b32_e32 v45, v169
	v_mov_b32_e32 v46, v169
	v_mov_b32_e32 v47, v169
	v_mov_b32_e32 v48, 0
	v_mov_b32_e32 v49, v169
	v_mov_b32_e32 v50, v169
	v_mov_b32_e32 v51, v169
	v_mov_b32_e32 v52, v169
	v_mov_b32_e32 v53, v169
	v_mov_b32_e32 v54, v169
	v_mov_b32_e32 v55, v169
	v_mov_b32_e32 v56, v169
	v_mov_b32_e32 v57, v169
	v_mov_b32_e32 v58, v169
	v_mov_b32_e32 v59, v169
	v_mov_b32_e32 v60, v169
	v_mov_b32_e32 v61, v169
	v_mov_b32_e32 v62, v169
	s_waitcnt vmcnt(8)
	s_mov_b32 s45, 0
	v_readfirstlane_b32 s100, v148
	s_nop 3
	v_subrev_u32_e32 v246, s100, v148
	v_add_u32_e32 v247, 0x10000, v246
	v_add_u32_e32 v248, 0x20000, v246
	v_add_u32_e32 v249, 0x30000, v246
	v_mov_b32_e32 v63, v169
; DI f32x16 mfma32(bf16x8 a, bf16x8 b, f32x16 c) { return __builtin_amdgcn_mfma_f32_32x32x16_bf16(a, b, c, 0, 0, 0); }
; DI void attn_diff_unit(const Params& p, int li, int b, int h, int qb, char* smem, bool pre, int nh, bool has_next) {
;     ...
;     const char* ks = smem + (kt & 1) * STG; const char* vs = ks + 128 * KR;
; #pragma unroll
;     for (int sub = 0; sub < 2; ++sub) {
;       const int kbase = kt * 128 + sub * 64;
;       const int relmin = kbase - (qb * 128 + 127), relmax = kbase + 63 - qb * 128;
;       const float cb = (relmin >= 128) ? cR : ((relmax <= -128) ? cL : 0.f);
;       f32x16 s0, s1;
; #pragma unroll
;       for (int i = 0; i < 16; ++i) { s0[i] = cb - m; s1[i] = cb - m; }
;       {
;         bf16x8 kf[8];
; #pragma unroll
;         for (int s = 0; s < 4; ++s) {
;           kf[2 * s] = *(const bf16x8*)(ks + (sub * 64 + r32) * KR + (map * 64 + s * 16 + hh * 8) * 2);
;           kf[2 * s + 1] = *(const bf16x8*)(ks + (sub * 64 + 32 + r32) * KR + (map * 64 + s * 16 + hh * 8) * 2);
;         }
;         __builtin_amdgcn_sched_barrier(0); __builtin_amdgcn_s_setprio(1);
; #pragma unroll
;         for (int s = 0; s < 4; ++s) { s0 = mfma32(kf[2 * s], qf[s], s0); s1 = mfma32(kf[2 * s + 1], qf[s], s1); }
;       __builtin_amdgcn_s_setprio(0);
; }
;       if (relmin < 128 && relmax > -128) {
;         const int base = kbase - qpos + 255 + 4 * hh;
; #pragma unroll
;         for (int i = 0; i < 16; ++i) {
;           int i0 = base + (i & 3) + 8 * (i >> 2);
;           int i1 = i0 + 32;
;           i0 = i0 < 0 ? 0 : (i0 > 510 ? 510 : i0);
;           i1 = i1 < 0 ? 0 : (i1 > 510 ? 510 : i1);
;           s0[i] += tab[i0]; s1[i] += tab[i1];
;         }
;       }
.LBB0_568:
	v_add_u32_e32 v76, s45, v167
	v_add_u32_e32 v174, v76, v165
	ds_read_b128 v[176:179], v174
	ds_read_b128 v[196:199], v174 offset:32
	ds_read_b128 v[200:203], v174 offset:8704
	ds_read_b128 v[204:207], v174 offset:8736
	ds_read_b128 v[208:211], v174 offset:64
	ds_read_b128 v[212:215], v174 offset:96
	ds_read_b128 v[216:219], v174 offset:8768
	ds_read_b128 v[220:223], v174 offset:8800
	s_add_i32 s44, s42, s24
	s_cmp_ge_i32 s44, 0xff
	s_cselect_b64 vcc, -1, 0
	s_cmp_le_i32 s44, 0xffffff41
	s_cselect_b64 s[2:3], -1, 0
	v_cndmask_b32_e64 v64, 0, v156, s[2:3]
	v_cndmask_b32_e32 v64, v64, v157, vcc
	v_sub_f32_e32 v64, v64, v169
	v_mov_b32_e32 v65, v64
	v_mov_b32_e32 v66, v64
	v_mov_b32_e32 v67, v64
	v_mov_b32_e32 v68, v64
	v_mov_b32_e32 v69, v64
	v_mov_b32_e32 v70, v64
	v_mov_b32_e32 v71, v64
	v_mov_b32_e32 v72, v64
	v_mov_b32_e32 v73, v64
	v_mov_b32_e32 v74, v64
	v_mov_b32_e32 v75, v64
	v_mov_b32_e32 v76, v64
	v_mov_b32_e32 v77, v64
	v_mov_b32_e32 v78, v64
	v_mov_b32_e32 v79, v64
	s_nop 0
	s_waitcnt lgkmcnt(4)
	v_mfma_f32_32x32x16_bf16 v[80:95], v[176:179], v[96:99], v[64:79]
	v_mfma_f32_32x32x16_bf16 v[64:79], v[200:203], v[96:99], v[64:79]
	v_mfma_f32_32x32x16_bf16 v[80:95], v[196:199], v[100:103], v[80:95]
	v_mfma_f32_32x32x16_bf16 v[64:79], v[204:207], v[100:103], v[64:79]
	s_waitcnt lgkmcnt(0)
	v_mfma_f32_32x32x16_bf16 v[80:95], v[208:211], v[104:107], v[80:95]
	v_mfma_f32_32x32x16_bf16 v[64:79], v[216:219], v[104:107], v[64:79]
	v_mfma_f32_32x32x16_bf16 v[80:95], v[212:215], v[108:111], v[80:95]
	v_mfma_f32_32x32x16_bf16 v[64:79], v[220:223], v[108:111], v[64:79]
	s_or_b64 s[2:3], s[2:3], vcc
	v_add_u32_e32 v173, s24, v168
	s_and_b64 vcc, exec, s[2:3]
	s_cbranch_vccnz .LBB0_570
	v_add_u32_e32 v177, 0x100, v173
	s_add_i32 s2, 0, 0x25000
	v_med3_i32 v178, v177, 0, v192
	v_med3_i32 v177, v177, s33, v193
	v_lshl_add_u32 v180, v177, 2, s2
	v_add_u32_e32 v177, 0x101, v173
	v_lshl_add_u32 v179, v178, 2, s2
	v_med3_i32 v178, v177, 0, v192
	v_med3_i32 v177, v177, s33, v193
	v_add_u32_e32 v199, 0x108, v173
	v_add_u32_e32 v175, 0xff, v173
	v_lshl_add_u32 v196, v177, 2, s2
	v_add_u32_e32 v177, 0x102, v173
	v_med3_i32 v200, v199, 0, v192
	v_med3_i32 v199, v199, s33, v193
	v_med3_i32 v176, v175, 0, v192
	v_med3_i32 v175, v175, s33, v193
	v_lshl_add_u32 v181, v178, 2, s2
	v_med3_i32 v178, v177, 0, v192
	v_lshl_add_u32 v202, v199, 2, s2
	v_add_u32_e32 v199, 0x109, v173
	v_lshl_add_u32 v176, v176, 2, s2
	v_lshl_add_u32 v175, v175, 2, s2
	v_med3_i32 v177, v177, s33, v193
	v_lshl_add_u32 v197, v178, 2, s2
	v_lshl_add_u32 v201, v200, 2, s2
	v_med3_i32 v200, v199, 0, v192
	v_med3_i32 v199, v199, s33, v193
	v_add_u32_e32 v207, 0x110, v173
	v_lshl_add_u32 v198, v177, 2, s2
	ds_read_b32 v176, v176
	ds_read_b32 v178, v175 offset:128
	ds_read_b32 v177, v179
	ds_read_b32 v179, v180 offset:128
	ds_read_b32 v180, v181
	ds_read_b32 v196, v196 offset:128
	ds_read_b32 v181, v197
	ds_read_b32 v197, v198 offset:128
	v_add_u32_e32 v175, 0x107, v173
	v_lshl_add_u32 v204, v199, 2, s2
	v_add_u32_e32 v199, 0x10a, v173
	v_med3_i32 v208, v207, 0, v192
	v_med3_i32 v207, v207, s33, v193
	v_med3_i32 v198, v175, 0, v192
	v_med3_i32 v175, v175, s33, v193
	v_lshl_add_u32 v203, v200, 2, s2
	v_med3_i32 v200, v199, 0, v192
	v_lshl_add_u32 v210, v207, 2, s2
	v_add_u32_e32 v207, 0x111, v173
	v_lshl_add_u32 v198, v198, 2, s2
	v_lshl_add_u32 v175, v175, 2, s2
	v_med3_i32 v199, v199, s33, v193
	v_lshl_add_u32 v205, v200, 2, s2
	v_lshl_add_u32 v209, v208, 2, s2
	v_med3_i32 v208, v207, 0, v192
	v_med3_i32 v207, v207, s33, v193
	v_add_u32_e32 v215, 0x118, v173
	v_lshl_add_u32 v206, v199, 2, s2
	ds_read_b32 v198, v198
	ds_read_b32 v200, v175 offset:128
	ds_read_b32 v199, v201
	ds_read_b32 v201, v202 offset:128
	ds_read_b32 v202, v203
	ds_read_b32 v204, v204 offset:128
	ds_read_b32 v203, v205
	ds_read_b32 v205, v206 offset:128
	v_add_u32_e32 v175, 0x10f, v173
	v_lshl_add_u32 v212, v207, 2, s2
	v_add_u32_e32 v207, 0x112, v173
	v_med3_i32 v216, v215, 0, v192
	v_med3_i32 v215, v215, s33, v193
	v_med3_i32 v206, v175, 0, v192
	v_med3_i32 v175, v175, s33, v193
	v_lshl_add_u32 v211, v208, 2, s2
	v_med3_i32 v208, v207, 0, v192
	v_lshl_add_u32 v222, v215, 2, s2
	v_add_u32_e32 v215, 0x119, v173
	v_lshl_add_u32 v206, v206, 2, s2
	v_lshl_add_u32 v175, v175, 2, s2
	v_med3_i32 v207, v207, s33, v193
	v_lshl_add_u32 v213, v208, 2, s2
	v_lshl_add_u32 v217, v216, 2, s2
	v_med3_i32 v216, v215, 0, v192
	v_med3_i32 v215, v215, s33, v193
	v_lshl_add_u32 v214, v207, 2, s2
	ds_read_b32 v206, v206
	ds_read_b32 v208, v175 offset:128
	ds_read_b32 v207, v209
	ds_read_b32 v209, v210 offset:128
	ds_read_b32 v210, v211
	ds_read_b32 v212, v212 offset:128
	ds_read_b32 v211, v213
	ds_read_b32 v213, v214 offset:128
	v_add_u32_e32 v175, 0x117, v173
	v_lshl_add_u32 v220, v215, 2, s2
	v_add_u32_e32 v215, 0x11a, v173
	v_med3_i32 v214, v175, 0, v192
	v_lshl_add_u32 v218, v216, 2, s2
	v_med3_i32 v216, v215, 0, v192
	v_med3_i32 v215, v215, s33, v193
	v_med3_i32 v175, v175, s33, v193
	v_lshl_add_u32 v214, v214, 2, s2
	v_lshl_add_u32 v219, v216, 2, s2
	v_lshl_add_u32 v221, v215, 2, s2
	v_lshl_add_u32 v175, v175, 2, s2
	ds_read_b32 v214, v214
	ds_read_b32 v216, v175 offset:128
	ds_read_b32 v218, v218
	ds_read_b32 v219, v219
	ds_read_b32 v215, v217
	ds_read_b32 v221, v221 offset:128
	ds_read_b32 v220, v220 offset:128
	ds_read_b32 v217, v222 offset:128
	s_waitcnt lgkmcnt(4)
	v_pk_add_f32 v[94:95], v[94:95], v[218:219]
	s_waitcnt lgkmcnt(3)
	v_pk_add_f32 v[92:93], v[92:93], v[214:215]
	v_pk_add_f32 v[90:91], v[90:91], v[210:211]
	v_pk_add_f32 v[88:89], v[88:89], v[206:207]
	v_pk_add_f32 v[86:87], v[86:87], v[202:203]
	v_pk_add_f32 v[84:85], v[84:85], v[198:199]
	v_pk_add_f32 v[82:83], v[82:83], v[180:181]
	v_pk_add_f32 v[80:81], v[80:81], v[176:177]
	s_waitcnt lgkmcnt(1)
	v_pk_add_f32 v[78:79], v[78:79], v[220:221]
	s_waitcnt lgkmcnt(0)
	v_pk_add_f32 v[76:77], v[76:77], v[216:217]
	v_pk_add_f32 v[74:75], v[74:75], v[212:213]
	v_pk_add_f32 v[72:73], v[72:73], v[208:209]
	v_pk_add_f32 v[70:71], v[70:71], v[204:205]
	v_pk_add_f32 v[68:69], v[68:69], v[200:201]
	v_pk_add_f32 v[66:67], v[66:67], v[196:197]
	v_pk_add_f32 v[64:65], v[64:65], v[178:179]

; DI f32x16 mfma32(bf16x8 a, bf16x8 b, f32x16 c) { return __builtin_amdgcn_mfma_f32_32x32x16_bf16(a, b, c, 0, 0, 0); }
; DI void attn_diff_unit(const Params& p, int li, int b, int h, int qb, char* smem, bool pre, int nh, bool has_next) {
;     ...
;       const int kbase = kt * 128 + sub * 64;
;       const int relmin = kbase - (qb * 128 + 127), relmax = kbase + 63 - qb * 128;
;       const float cb = (relmin >= 128) ? cR : ((relmax <= -128) ? cL : 0.f);
;       f32x16 s0, s1;
; #pragma unroll
;       for (int i = 0; i < 16; ++i) { s0[i] = cb - m; s1[i] = cb - m; }
;       {
;         bf16x8 kf[8];
; #pragma unroll
;         for (int s = 0; s < 4; ++s) {
;           kf[2 * s] = *(const bf16x8*)(ks + (sub * 64 + r32) * KR + (map * 64 + s * 16 + hh * 8) * 2);
;           kf[2 * s + 1] = *(const bf16x8*)(ks + (sub * 64 + 32 + r32) * KR + (map * 64 + s * 16 + hh * 8) * 2);
;         }
;         __builtin_amdgcn_sched_barrier(0); __builtin_amdgcn_s_setprio(1);
; #pragma unroll
;         for (int s = 0; s < 4; ++s) { s0 = mfma32(kf[2 * s], qf[s], s0); s1 = mfma32(kf[2 * s + 1], qf[s], s1); }
;       __builtin_amdgcn_s_setprio(0);
; }
;       if (relmin < 128 && relmax > -128) {
;         const int base = kbase - qpos + 255 + 4 * hh;
; #pragma unroll
;         for (int i = 0; i < 16; ++i) {
;           int i0 = base + (i & 3) + 8 * (i >> 2);
;           int i1 = i0 + 32;
;           i0 = i0 < 0 ? 0 : (i0 > 510 ? 510 : i0);
;           i1 = i1 < 0 ? 0 : (i1 > 510 ? 510 : i1);
;           s0[i] += tab[i0]; s1[i] += tab[i1];
;         }
;       }
.Ldp_ck_done:
	v_cvt_pk_bf16_f32 v64, v64, v65
	v_cvt_pk_bf16_f32 v65, v66, v67
	v_cvt_pk_bf16_f32 v66, v68, v69
	v_cvt_pk_bf16_f32 v67, v70, v71
	v_cvt_pk_bf16_f32 v68, v72, v73
	v_cvt_pk_bf16_f32 v69, v74, v75
	v_cvt_pk_bf16_f32 v70, v76, v77
	v_cvt_pk_bf16_f32 v71, v78, v79
	v_cvt_pk_bf16_f32 v72, v80, v81
	v_cvt_pk_bf16_f32 v73, v82, v83
	v_cvt_pk_bf16_f32 v74, v84, v85
	v_cvt_pk_bf16_f32 v75, v86, v87
	v_cvt_pk_bf16_f32 v76, v88, v89
	v_cvt_pk_bf16_f32 v77, v90, v91
	v_cvt_pk_bf16_f32 v78, v92, v93
	v_cvt_pk_bf16_f32 v79, v94, v95
	s_add_i32 s2, s44, 64
	s_cmp_ge_i32 s2, 0xff
	s_cselect_b64 vcc, -1, 0
	s_cmp_le_i32 s2, 0xffffff41
	s_cselect_b64 s[2:3], -1, 0
	v_cndmask_b32_e64 v196, 0, v156, s[2:3]
	v_cndmask_b32_e32 v196, v196, v157, vcc
	v_sub_f32_e32 v196, v196, v169
	v_mov_b32_e32 v197, v196
	v_mov_b32_e32 v198, v196
	v_mov_b32_e32 v199, v196
	v_mov_b32_e32 v200, v196
	v_mov_b32_e32 v201, v196
	v_mov_b32_e32 v202, v196
	v_mov_b32_e32 v203, v196
	v_mov_b32_e32 v204, v196
	v_mov_b32_e32 v205, v196
	v_mov_b32_e32 v206, v196
	v_mov_b32_e32 v207, v196
	v_mov_b32_e32 v208, v196
	v_mov_b32_e32 v209, v196
	v_mov_b32_e32 v210, v196
	v_mov_b32_e32 v211, v196
	s_waitcnt lgkmcnt(0)
	s_nop 0
	v_mfma_f32_32x32x16_bf16 v[80:95], v[212:215], v[96:99], v[196:211]
	v_mfma_f32_32x32x16_bf16 v[196:211], v[216:219], v[96:99], v[196:211]
	v_mfma_f32_32x32x16_bf16 v[80:95], v[220:223], v[100:103], v[80:95]
	v_mfma_f32_32x32x16_bf16 v[196:211], v[224:227], v[100:103], v[196:211]
	v_mfma_f32_32x32x16_bf16 v[80:95], v[228:231], v[104:107], v[80:95]
	v_mfma_f32_32x32x16_bf16 v[196:211], v[232:235], v[104:107], v[196:211]
	v_mfma_f32_32x32x16_bf16 v[80:95], v[176:179], v[108:111], v[80:95]
	v_mfma_f32_32x32x16_bf16 v[196:211], v[242:245], v[108:111], v[196:211]
	s_or_b64 s[2:3], s[2:3], vcc
	s_and_b64 vcc, exec, s[2:3]
	s_cbranch_vccnz .Ldp_b1_skip
	s_add_i32 s2, 0, 0x25000
	v_add_u32_e32 v212, 0x13f, v173
	v_add_u32_e32 v228, 0x13f, v173
	v_add_u32_e32 v213, 0x140, v173
	v_add_u32_e32 v229, 0x140, v173
	v_add_u32_e32 v214, 0x141, v173
	v_add_u32_e32 v230, 0x141, v173
	v_add_u32_e32 v215, 0x142, v173
	v_add_u32_e32 v231, 0x142, v173
	v_add_u32_e32 v216, 0x147, v173
	v_add_u32_e32 v232, 0x147, v173
	v_add_u32_e32 v217, 0x148, v173
	v_add_u32_e32 v233, 0x148, v173
	v_add_u32_e32 v218, 0x149, v173
	v_add_u32_e32 v234, 0x149, v173
	v_add_u32_e32 v219, 0x14a, v173
	v_add_u32_e32 v235, 0x14a, v173
	v_add_u32_e32 v220, 0x14f, v173
	v_add_u32_e32 v176, 0x14f, v173
	v_add_u32_e32 v221, 0x150, v173
	v_add_u32_e32 v177, 0x150, v173
	v_add_u32_e32 v222, 0x151, v173
	v_add_u32_e32 v178, 0x151, v173
	v_add_u32_e32 v223, 0x152, v173
	v_add_u32_e32 v179, 0x152, v173
	v_add_u32_e32 v224, 0x157, v173
	v_add_u32_e32 v242, 0x157, v173
	v_add_u32_e32 v225, 0x158, v173
	v_add_u32_e32 v243, 0x158, v173
	v_add_u32_e32 v226, 0x159, v173
	v_add_u32_e32 v244, 0x159, v173
	v_add_u32_e32 v227, 0x15a, v173
	v_add_u32_e32 v245, 0x15a, v173
	v_med3_i32 v212, v212, 0, v192
	v_med3_i32 v228, v228, s33, v193
	v_med3_i32 v213, v213, 0, v192
	v_med3_i32 v229, v229, s33, v193
	v_med3_i32 v214, v214, 0, v192
	v_med3_i32 v230, v230, s33, v193
	v_med3_i32 v215, v215, 0, v192
	v_med3_i32 v231, v231, s33, v193
	v_med3_i32 v216, v216, 0, v192
	v_med3_i32 v232, v232, s33, v193
	v_med3_i32 v217, v217, 0, v192
	v_med3_i32 v233, v233, s33, v193
	v_med3_i32 v218, v218, 0, v192
	v_med3_i32 v234, v234, s33, v193
	v_med3_i32 v219, v219, 0, v192
	v_med3_i32 v235, v235, s33, v193
	v_med3_i32 v220, v220, 0, v192
	v_med3_i32 v176, v176, s33, v193
	v_med3_i32 v221, v221, 0, v192
	v_med3_i32 v177, v177, s33, v193
	v_med3_i32 v222, v222, 0, v192
	v_med3_i32 v178, v178, s33, v193
	v_med3_i32 v223, v223, 0, v192
	v_med3_i32 v179, v179, s33, v193
	v_med3_i32 v224, v224, 0, v192
	v_med3_i32 v242, v242, s33, v193
	v_med3_i32 v225, v225, 0, v192
	v_med3_i32 v243, v243, s33, v193
	v_med3_i32 v226, v226, 0, v192
	v_med3_i32 v244, v244, s33, v193
	v_med3_i32 v227, v227, 0, v192
	v_med3_i32 v245, v245, s33, v193
	v_lshl_add_u32 v212, v212, 2, s2
	v_lshl_add_u32 v228, v228, 2, s2
	v_lshl_add_u32 v213, v213, 2, s2
	v_lshl_add_u32 v229, v229, 2, s2
	v_lshl_add_u32 v214, v214, 2, s2
	v_lshl_add_u32 v230, v230, 2, s2
	v_lshl_add_u32 v215, v215, 2, s2
	v_lshl_add_u32 v231, v231, 2, s2
	v_lshl_add_u32 v216, v216, 2, s2
	v_lshl_add_u32 v232, v232, 2, s2
	v_lshl_add_u32 v217, v217, 2, s2
	v_lshl_add_u32 v233, v233, 2, s2
	v_lshl_add_u32 v218, v218, 2, s2
	v_lshl_add_u32 v234, v234, 2, s2
	v_lshl_add_u32 v219, v219, 2, s2
	v_lshl_add_u32 v235, v235, 2, s2
	v_lshl_add_u32 v220, v220, 2, s2
	v_lshl_add_u32 v176, v176, 2, s2
	v_lshl_add_u32 v221, v221, 2, s2
	v_lshl_add_u32 v177, v177, 2, s2
	v_lshl_add_u32 v222, v222, 2, s2
	v_lshl_add_u32 v178, v178, 2, s2
	v_lshl_add_u32 v223, v223, 2, s2
	v_lshl_add_u32 v179, v179, 2, s2
	v_lshl_add_u32 v224, v224, 2, s2
	v_lshl_add_u32 v242, v242, 2, s2
	v_lshl_add_u32 v225, v225, 2, s2
	v_lshl_add_u32 v243, v243, 2, s2
	v_lshl_add_u32 v226, v226, 2, s2
	v_lshl_add_u32 v244, v244, 2, s2
	v_lshl_add_u32 v227, v227, 2, s2
	v_lshl_add_u32 v245, v245, 2, s2
	ds_read_b32 v212, v212
	ds_read_b32 v228, v228 offset:128
	ds_read_b32 v213, v213
	ds_read_b32 v229, v229 offset:128
	ds_read_b32 v214, v214
	ds_read_b32 v230, v230 offset:128
	ds_read_b32 v215, v215
	ds_read_b32 v231, v231 offset:128
	ds_read_b32 v216, v216
	ds_read_b32 v232, v232 offset:128
	ds_read_b32 v217, v217
	ds_read_b32 v233, v233 offset:128
	ds_read_b32 v218, v218
	ds_read_b32 v234, v234 offset:128
	ds_read_b32 v219, v219
	ds_read_b32 v235, v235 offset:128
	ds_read_b32 v220, v220
	ds_read_b32 v176, v176 offset:128
	ds_read_b32 v221, v221
	ds_read_b32 v177, v177 offset:128
	ds_read_b32 v222, v222
	ds_read_b32 v178, v178 offset:128
	ds_read_b32 v223, v223
	ds_read_b32 v179, v179 offset:128
	ds_read_b32 v224, v224
	ds_read_b32 v242, v242 offset:128
	ds_read_b32 v225, v225
	ds_read_b32 v243, v243 offset:128
	ds_read_b32 v226, v226
	ds_read_b32 v244, v244 offset:128
	ds_read_b32 v227, v227
	ds_read_b32 v245, v245 offset:128
	s_waitcnt lgkmcnt(0)
	v_add_f32_e32 v80, v80, v212
	v_add_f32_e32 v196, v196, v228
	v_add_f32_e32 v81, v81, v213
	v_add_f32_e32 v197, v197, v229
	v_add_f32_e32 v82, v82, v214
	v_add_f32_e32 v198, v198, v230
	v_add_f32_e32 v83, v83, v215
	v_add_f32_e32 v199, v199, v231
	v_add_f32_e32 v84, v84, v216
	v_add_f32_e32 v200, v200, v232
	v_add_f32_e32 v85, v85, v217
	v_add_f32_e32 v201, v201, v233
	v_add_f32_e32 v86, v86, v218
	v_add_f32_e32 v202, v202, v234
	v_add_f32_e32 v87, v87, v219
	v_add_f32_e32 v203, v203, v235
	v_add_f32_e32 v88, v88, v220
	v_add_f32_e32 v204, v204, v176
	v_add_f32_e32 v89, v89, v221
	v_add_f32_e32 v205, v205, v177
	v_add_f32_e32 v90, v90, v222
	v_add_f32_e32 v206, v206, v178
	v_add_f32_e32 v91, v91, v223
	v_add_f32_e32 v207, v207, v179
	v_add_f32_e32 v92, v92, v224
	v_add_f32_e32 v208, v208, v242
	v_add_f32_e32 v93, v93, v225
	v_add_f32_e32 v209, v209, v243
	v_add_f32_e32 v94, v94, v226
	v_add_f32_e32 v210, v210, v244
	v_add_f32_e32 v95, v95, v227
	v_add_f32_e32 v211, v211, v245
; DI f32x16 mfma32(bf16x8 a, bf16x8 b, f32x16 c) { return __builtin_amdgcn_mfma_f32_32x32x16_bf16(a, b, c, 0, 0, 0); }
; DI bool softmax_tile(f32x16& s0, f32x16& s1, float& m, float& l, float& alpha, bf16x8* pf, int lane, bool first, bool check) {
;     ...
;   float sum = 0.f;
; #pragma unroll
;   for (int i = 0; i < 16; ++i) { s0[i] = __builtin_amdgcn_exp2f(s0[i]); sum += s0[i]; }
; #pragma unroll
;   for (int i = 0; i < 16; ++i) { s1[i] = __builtin_amdgcn_exp2f(s1[i]); sum += s1[i]; }
;   l += sum;
;   pf[0] = pack8(s0, 0); pf[1] = pack8(s0, 8); pf[2] = pack8(s1, 0); pf[3] = pack8(s1, 8);
; DI void attn_diff_unit(const Params& p, int li, int b, int h, int qb, char* smem, bool pre, int nh, bool has_next) {
;     ...
;       const bool resc = softmax_tile(s0, s1, m, l, alpha, pf, lane, (kt == 0) && (sub == 0), (sub == 0) && ((kt & 3) == 0));
;       {
;         bf16x8 vf[2][4];
; #pragma unroll
;         for (int j = 0; j < 4; ++j) vf[0][j] = ld_vfrag_tr(vs, vbase, VR, sub * 64, j * 32);
; #pragma unroll
;         for (int s = 0; s < 4; ++s) {
;           if (s < 3) {
; #pragma unroll
;             for (int j = 0; j < 4; ++j) vf[(s + 1) & 1][j] = ld_vfrag_tr(vs, vbase, VR, sub * 64 + 16 * (s + 1), j * 32);
;           }
;           __builtin_amdgcn_sched_barrier(0); __builtin_amdgcn_s_setprio(1);
; #pragma unroll
;           for (int j = 0; j < 4; ++j) O[j] = mfma32(vf[s & 1][j], pf[s], O[j]);
;         __builtin_amdgcn_s_setprio(0);
; }
.Ldp_b1_skip:
	ds_read_b64_tr_b16 v[212:213], v175 offset:34816
	ds_read_b64_tr_b16 v[214:215], v175 offset:37376
	ds_read_b64_tr_b16 v[216:217], v175 offset:34880
	ds_read_b64_tr_b16 v[218:219], v175 offset:37440
	ds_read_b64_tr_b16 v[220:221], v175 offset:34944
	ds_read_b64_tr_b16 v[222:223], v175 offset:37504
	ds_read_b64_tr_b16 v[224:225], v175 offset:35008
	ds_read_b64_tr_b16 v[226:227], v175 offset:37568
	ds_read_b64_tr_b16 v[228:229], v175 offset:39936
	ds_read_b64_tr_b16 v[230:231], v175 offset:42496
	ds_read_b64_tr_b16 v[232:233], v175 offset:40000
	ds_read_b64_tr_b16 v[234:235], v175 offset:42560
	ds_read_b64_tr_b16 v[176:177], v175 offset:40064
	ds_read_b64_tr_b16 v[178:179], v175 offset:42624
	ds_read_b64_tr_b16 v[242:243], v175 offset:40128
	ds_read_b64_tr_b16 v[244:245], v175 offset:42688
	s_waitcnt lgkmcnt(8)
	v_mfma_f32_32x32x16_bf16 v[48:63], v[212:215], v[72:75], v[48:63]
	v_exp_f32_e32 v80, v80
	v_exp_f32_e32 v81, v81
	v_mfma_f32_32x32x16_bf16 v[32:47], v[216:219], v[72:75], v[32:47]
	v_exp_f32_e32 v82, v82
	v_exp_f32_e32 v83, v83
	v_add_f32_e32 v253, 0, v80
	v_add_f32_e32 v253, v81, v253
	v_mfma_f32_32x32x16_bf16 v[16:31], v[220:223], v[72:75], v[16:31]
	v_exp_f32_e32 v84, v84
	v_exp_f32_e32 v85, v85
	v_add_f32_e32 v253, v82, v253
	v_add_f32_e32 v253, v83, v253
	v_mfma_f32_32x32x16_bf16 v[0:15], v[224:227], v[72:75], v[0:15]
	v_exp_f32_e32 v86, v86
	v_exp_f32_e32 v87, v87
	v_add_f32_e32 v253, v84, v253
	v_add_f32_e32 v253, v85, v253
	ds_read_b64_tr_b16 v[212:213], v175 offset:45056
	ds_read_b64_tr_b16 v[214:215], v175 offset:47616
	ds_read_b64_tr_b16 v[216:217], v175 offset:45120
	ds_read_b64_tr_b16 v[218:219], v175 offset:47680
	ds_read_b64_tr_b16 v[220:221], v175 offset:45184
	ds_read_b64_tr_b16 v[222:223], v175 offset:47744
	ds_read_b64_tr_b16 v[224:225], v175 offset:45248
	ds_read_b64_tr_b16 v[226:227], v175 offset:47808
	s_waitcnt lgkmcnt(8)
	v_mfma_f32_32x32x16_bf16 v[48:63], v[228:231], v[76:79], v[48:63]
	v_exp_f32_e32 v88, v88
	v_exp_f32_e32 v89, v89
	v_add_f32_e32 v253, v86, v253
	v_add_f32_e32 v253, v87, v253
	v_cvt_pk_bf16_f32 v80, v80, v81
	v_mfma_f32_32x32x16_bf16 v[32:47], v[232:235], v[76:79], v[32:47]
	v_exp_f32_e32 v90, v90
	v_exp_f32_e32 v91, v91
	v_add_f32_e32 v253, v88, v253
	v_add_f32_e32 v253, v89, v253
	v_cvt_pk_bf16_f32 v81, v82, v83
	v_mfma_f32_32x32x16_bf16 v[16:31], v[176:179], v[76:79], v[16:31]
	v_exp_f32_e32 v92, v92
	v_exp_f32_e32 v93, v93
	v_add_f32_e32 v253, v90, v253
	v_add_f32_e32 v253, v91, v253
	v_cvt_pk_bf16_f32 v82, v84, v85
	v_mfma_f32_32x32x16_bf16 v[0:15], v[242:245], v[76:79], v[0:15]
	v_exp_f32_e32 v94, v94
	v_exp_f32_e32 v95, v95
	v_add_f32_e32 v253, v92, v253
	v_add_f32_e32 v253, v93, v253
	v_cvt_pk_bf16_f32 v83, v86, v87
	ds_read_b64_tr_b16 v[228:229], v175 offset:50176
	ds_read_b64_tr_b16 v[230:231], v175 offset:52736
	ds_read_b64_tr_b16 v[232:233], v175 offset:50240
	ds_read_b64_tr_b16 v[234:235], v175 offset:52800
	ds_read_b64_tr_b16 v[176:177], v175 offset:50304
	ds_read_b64_tr_b16 v[178:179], v175 offset:52864
	ds_read_b64_tr_b16 v[242:243], v175 offset:50368
	ds_read_b64_tr_b16 v[244:245], v175 offset:52928
	s_waitcnt lgkmcnt(8)
	v_mfma_f32_32x32x16_bf16 v[48:63], v[212:215], v[64:67], v[48:63]
	v_exp_f32_e32 v196, v196
	v_exp_f32_e32 v197, v197
	v_add_f32_e32 v253, v94, v253
	v_add_f32_e32 v253, v95, v253
	v_cvt_pk_bf16_f32 v84, v88, v89
	v_mfma_f32_32x32x16_bf16 v[32:47], v[216:219], v[64:67], v[32:47]
	v_exp_f32_e32 v198, v198
	v_exp_f32_e32 v199, v199
	v_add_f32_e32 v253, v196, v253
	v_add_f32_e32 v253, v197, v253
	v_cvt_pk_bf16_f32 v85, v90, v91
	v_mfma_f32_32x32x16_bf16 v[16:31], v[220:223], v[64:67], v[16:31]
	v_exp_f32_e32 v200, v200
	v_exp_f32_e32 v201, v201
	v_add_f32_e32 v253, v198, v253
	v_add_f32_e32 v253, v199, v253
	v_cvt_pk_bf16_f32 v86, v92, v93
	v_mfma_f32_32x32x16_bf16 v[0:15], v[224:227], v[64:67], v[0:15]
	v_exp_f32_e32 v202, v202
	v_exp_f32_e32 v203, v203
	v_add_f32_e32 v253, v200, v253
	v_add_f32_e32 v253, v201, v253
	v_cvt_pk_bf16_f32 v87, v94, v95
	s_waitcnt lgkmcnt(0)
	v_mfma_f32_32x32x16_bf16 v[48:63], v[228:231], v[68:71], v[48:63]
	v_exp_f32_e32 v204, v204
	v_exp_f32_e32 v205, v205
	v_add_f32_e32 v253, v202, v253
	v_add_f32_e32 v253, v203, v253
	v_cvt_pk_bf16_f32 v196, v196, v197
	v_mfma_f32_32x32x16_bf16 v[32:47], v[232:235], v[68:71], v[32:47]
	v_exp_f32_e32 v206, v206
	v_exp_f32_e32 v207, v207
	v_add_f32_e32 v253, v204, v253
	v_add_f32_e32 v253, v205, v253
	v_cvt_pk_bf16_f32 v197, v198, v199
	v_mfma_f32_32x32x16_bf16 v[16:31], v[176:179], v[68:71], v[16:31]
	v_exp_f32_e32 v208, v208
	v_exp_f32_e32 v209, v209
	v_add_f32_e32 v253, v206, v253
	v_add_f32_e32 v253, v207, v253
	v_cvt_pk_bf16_f32 v198, v200, v201
	v_mfma_f32_32x32x16_bf16 v[0:15], v[242:245], v[68:71], v[0:15]
	v_exp_f32_e32 v210, v210
	v_exp_f32_e32 v211, v211
	v_add_f32_e32 v253, v208, v253
	v_add_f32_e32 v253, v209, v253
	v_cvt_pk_bf16_f32 v199, v202, v203
	v_add_f32_e32 v253, v210, v253
	v_add_f32_e32 v253, v211, v253
	v_cvt_pk_bf16_f32 v200, v204, v205
	v_cvt_pk_bf16_f32 v201, v206, v207
	v_cvt_pk_bf16_f32 v202, v208, v209
	v_cvt_pk_bf16_f32 v203, v210, v211
	v_add_f32_e32 v172, v172, v253
	s_andn2_b64 vcc, exec, s[100:101]
	s_cbranch_vccnz .Ldp_nors
; DI f32x16 mfma32(bf16x8 a, bf16x8 b, f32x16 c) { return __builtin_amdgcn_mfma_f32_32x32x16_bf16(a, b, c, 0, 0, 0); }
; DI void attn_diff_unit(const Params& p, int li, int b, int h, int qb, char* smem, bool pre, int nh, bool has_next) {
;     ...
;       {
;         bf16x8 vf[2][4];
; #pragma unroll
;         for (int j = 0; j < 4; ++j) vf[0][j] = ld_vfrag_tr(vs, vbase, VR, sub * 64, j * 32);
; #pragma unroll
;         for (int s = 0; s < 4; ++s) {
;           if (s < 3) {
; #pragma unroll
;             for (int j = 0; j < 4; ++j) vf[(s + 1) & 1][j] = ld_vfrag_tr(vs, vbase, VR, sub * 64 + 16 * (s + 1), j * 32);
;           }
;           __builtin_amdgcn_sched_barrier(0); __builtin_amdgcn_s_setprio(1);
; #pragma unroll
;           for (int j = 0; j < 4; ++j) O[j] = mfma32(vf[s & 1][j], pf[s], O[j]);
;         __builtin_amdgcn_s_setprio(0);
; }
;       }
;       if (resc) {
; #pragma unroll
;         for (int j = 0; j < 4; ++j) scale16(O[j], alpha);
;       }
;     }
;     if (kt + 1 < 32) put_stage(smem + ((kt + 1) & 1) * STG);
	s_nop 15
	v_mul_f32_e32 v0, v0, v252
	v_mul_f32_e32 v1, v1, v252
	v_mul_f32_e32 v2, v2, v252
	v_mul_f32_e32 v3, v3, v252
	v_mul_f32_e32 v4, v4, v252
	v_mul_f32_e32 v5, v5, v252
	v_mul_f32_e32 v6, v6, v252
	v_mul_f32_e32 v7, v7, v252
	v_mul_f32_e32 v8, v8, v252
	v_mul_f32_e32 v9, v9, v252
	v_mul_f32_e32 v10, v10, v252
	v_mul_f32_e32 v11, v11, v252
	v_mul_f32_e32 v12, v12, v252
	v_mul_f32_e32 v13, v13, v252
	v_mul_f32_e32 v14, v14, v252
	v_mul_f32_e32 v15, v15, v252
	v_mul_f32_e32 v16, v16, v252
	v_mul_f32_e32 v17, v17, v252
	v_mul_f32_e32 v18, v18, v252
	v_mul_f32_e32 v19, v19, v252
	v_mul_f32_e32 v20, v20, v252
	v_mul_f32_e32 v21, v21, v252
	v_mul_f32_e32 v22, v22, v252
	v_mul_f32_e32 v23, v23, v252
	v_mul_f32_e32 v24, v24, v252
	v_mul_f32_e32 v25, v25, v252
	v_mul_f32_e32 v26, v26, v252
	v_mul_f32_e32 v27, v27, v252
	v_mul_f32_e32 v28, v28, v252
	v_mul_f32_e32 v29, v29, v252
	v_mul_f32_e32 v30, v30, v252
	v_mul_f32_e32 v31, v31, v252
	v_mul_f32_e32 v32, v32, v252
	v_mul_f32_e32 v33, v33, v252
	v_mul_f32_e32 v34, v34, v252
	v_mul_f32_e32 v35, v35, v252
	v_mul_f32_e32 v36, v36, v252
	v_mul_f32_e32 v37, v37, v252
	v_mul_f32_e32 v38, v38, v252
	v_mul_f32_e32 v39, v39, v252
	v_mul_f32_e32 v40, v40, v252
	v_mul_f32_e32 v41, v41, v252
	v_mul_f32_e32 v42, v42, v252
	v_mul_f32_e32 v43, v43, v252
	v_mul_f32_e32 v44, v44, v252
	v_mul_f32_e32 v45, v45, v252
	v_mul_f32_e32 v46, v46, v252
	v_mul_f32_e32 v47, v47, v252
	v_mul_f32_e32 v48, v48, v252
	v_mul_f32_e32 v49, v49, v252
	v_mul_f32_e32 v50, v50, v252
	v_mul_f32_e32 v51, v51, v252
	v_mul_f32_e32 v52, v52, v252
	v_mul_f32_e32 v53, v53, v252
	v_mul_f32_e32 v54, v54, v252
	v_mul_f32_e32 v55, v55, v252
	v_mul_f32_e32 v56, v56, v252
	v_mul_f32_e32 v57, v57, v252
	v_mul_f32_e32 v58, v58, v252
	v_mul_f32_e32 v59, v59, v252
	v_mul_f32_e32 v60, v60, v252
	v_mul_f32_e32 v61, v61, v252
	v_mul_f32_e32 v62, v62, v252
	v_mul_f32_e32 v63, v63, v252
.Ldp_nors:
	ds_read_b64_tr_b16 v[212:213], v175 offset:55296
	ds_read_b64_tr_b16 v[214:215], v175 offset:57856
	ds_read_b64_tr_b16 v[216:217], v175 offset:55360
	ds_read_b64_tr_b16 v[218:219], v175 offset:57920
	ds_read_b64_tr_b16 v[220:221], v175 offset:55424
	ds_read_b64_tr_b16 v[222:223], v175 offset:57984
	ds_read_b64_tr_b16 v[224:225], v175 offset:55488
	ds_read_b64_tr_b16 v[226:227], v175 offset:58048
	ds_read_b64_tr_b16 v[228:229], v175 offset:60416
	ds_read_b64_tr_b16 v[230:231], v175 offset:62976
	ds_read_b64_tr_b16 v[232:233], v175 offset:60480
	ds_read_b64_tr_b16 v[234:235], v175 offset:63040
	ds_read_b64_tr_b16 v[176:177], v175 offset:60544
	ds_read_b64_tr_b16 v[178:179], v175 offset:63104
	ds_read_b64_tr_b16 v[242:243], v175 offset:60608
	ds_read_b64_tr_b16 v[244:245], v175 offset:63168
	s_waitcnt lgkmcnt(8)
	v_mfma_f32_32x32x16_bf16 v[48:63], v[212:215], v[80:83], v[48:63]
	v_mfma_f32_32x32x16_bf16 v[32:47], v[216:219], v[80:83], v[32:47]
	v_mfma_f32_32x32x16_bf16 v[16:31], v[220:223], v[80:83], v[16:31]
	v_mfma_f32_32x32x16_bf16 v[0:15], v[224:227], v[80:83], v[0:15]
	ds_read_b64_tr_b16 v[212:213], v236 offset:30720
	ds_read_b64_tr_b16 v[214:215], v236 offset:33280
	ds_read_b64_tr_b16 v[216:217], v236 offset:30784
	ds_read_b64_tr_b16 v[218:219], v236 offset:33344
	ds_read_b64_tr_b16 v[220:221], v236 offset:30848
	ds_read_b64_tr_b16 v[222:223], v236 offset:33408
	ds_read_b64_tr_b16 v[224:225], v236 offset:30912
	ds_read_b64_tr_b16 v[226:227], v236 offset:33472
	s_waitcnt lgkmcnt(8)
	v_mfma_f32_32x32x16_bf16 v[48:63], v[228:231], v[84:87], v[48:63]
	v_mfma_f32_32x32x16_bf16 v[32:47], v[232:235], v[84:87], v[32:47]
	v_mfma_f32_32x32x16_bf16 v[16:31], v[176:179], v[84:87], v[16:31]
	v_mfma_f32_32x32x16_bf16 v[0:15], v[242:245], v[84:87], v[0:15]
	ds_read_b64_tr_b16 v[228:229], v236 offset:35840
	ds_read_b64_tr_b16 v[230:231], v236 offset:38400
	ds_read_b64_tr_b16 v[232:233], v236 offset:35904
	ds_read_b64_tr_b16 v[234:235], v236 offset:38464
	ds_read_b64_tr_b16 v[176:177], v236 offset:35968
	ds_read_b64_tr_b16 v[178:179], v236 offset:38528
	ds_read_b64_tr_b16 v[242:243], v236 offset:36032
	ds_read_b64_tr_b16 v[244:245], v236 offset:38592
	s_waitcnt lgkmcnt(8)
	v_mfma_f32_32x32x16_bf16 v[48:63], v[212:215], v[196:199], v[48:63]
	v_mfma_f32_32x32x16_bf16 v[32:47], v[216:219], v[196:199], v[32:47]
	v_mfma_f32_32x32x16_bf16 v[16:31], v[220:223], v[196:199], v[16:31]
	v_mfma_f32_32x32x16_bf16 v[0:15], v[224:227], v[196:199], v[0:15]
	s_waitcnt lgkmcnt(0)
	v_mfma_f32_32x32x16_bf16 v[48:63], v[228:231], v[200:203], v[48:63]
	v_mfma_f32_32x32x16_bf16 v[32:47], v[232:235], v[200:203], v[32:47]
	v_mfma_f32_32x32x16_bf16 v[16:31], v[176:179], v[200:203], v[16:31]
	v_mfma_f32_32x32x16_bf16 v[0:15], v[242:245], v[200:203], v[0:15]
	s_add_i32 s44, s43, 1
	s_cmpk_eq_i32 s24, 0xf80
	s_mov_b64 s[2:3], -1
	s_cbranch_scc1 .LBB0_583
	s_xor_b32 s2, s45, 0x12800
	v_add3_u32 v64, s2, v161, v159
	v_add3_u32 v65, s2, v160, v159
	s_mov_b64 s[2:3], 0
	s_waitcnt vmcnt(3)
	ds_write_b128 v64, v[116:119]
	v_add_u32_e32 v66, 0x8800, v65
	s_waitcnt vmcnt(1)
	ds_write_b128 v65, v[128:131] offset:34816
	s_waitcnt vmcnt(5)
	ds_write_b128 v64, v[112:115] offset:8704
	s_waitcnt vmcnt(4)
	ds_write_b128 v65, v[120:123] offset:45056
	s_waitcnt vmcnt(3)
	ds_write_b128 v64, v[124:127] offset:17408
	s_waitcnt vmcnt(2)
	ds_write_b128 v65, v[132:135] offset:55296
	s_waitcnt vmcnt(1)
	ds_write_b128 v64, v[136:139] offset:26112
	s_waitcnt vmcnt(0)
	ds_write_b128 v66, v[140:143] offset:30720

; DI void attn_diff_unit(const Params& p, int li, int b, int h, int qb, char* smem, bool pre, int nh, bool has_next) {
;     ...
;     __syncthreads();
;     if (kt + 2 < 32) get_stage(kt + 2);
;     else if (kt == 30 && has_next) { gk += (nh - h) * 128; gv += (nh - h) * 128; get_stage(0); }
.LBB0_586:
	s_cmp_gt_u32 s43, 29
	s_mov_b64 s[2:3], -1
	s_waitcnt lgkmcnt(0)
	s_barrier
	s_cbranch_scc0 .LBB0_590
	s_cmpk_lg_i32 s24, 0xf00
	s_cselect_b64 s[2:3], -1, 0
	s_xor_b64 s[46:47], s[28:29], -1
	s_or_b64 s[2:3], s[46:47], s[2:3]
	s_and_b64 vcc, exec, s[2:3]
	v_mov_b64_e32 v[64:65], v[148:149]
	v_mov_b64_e32 v[66:67], v[150:151]
	s_cbranch_vccnz .LBB0_589
	v_lshl_add_u64 v[64:65], v[148:149], 0, s[36:37]
	s_waitcnt vmcnt(5)
	v_add_co_u32_e32 v112, vcc, 0x10000, v64
	v_lshl_add_u64 v[66:67], v[150:151], 0, s[36:37]
	s_nop 0
	v_addc_co_u32_e32 v113, vcc, 0, v65, vcc
	s_waitcnt vmcnt(4)
	v_add_co_u32_e32 v120, vcc, 0x10000, v66
	global_load_dwordx4 v[116:119], v[64:65], off
	s_nop 0
	v_addc_co_u32_e32 v121, vcc, 0, v67, vcc
	s_waitcnt vmcnt(4)
	v_add_co_u32_e32 v124, vcc, 0x20000, v64
	global_load_dwordx4 v[112:115], v[112:113], off
	s_nop 0
	v_addc_co_u32_e32 v125, vcc, 0, v65, vcc
	s_waitcnt vmcnt(3)
	v_add_co_u32_e32 v128, vcc, 0x20000, v66
	global_load_dwordx4 v[120:123], v[120:121], off
	s_nop 0
	v_addc_co_u32_e32 v129, vcc, 0, v67, vcc
	global_load_dwordx4 v[132:135], v[128:129], off
	v_add_co_u32_e32 v128, vcc, 0x30000, v64
	global_load_dwordx4 v[124:127], v[124:125], off
	s_nop 0
	v_addc_co_u32_e32 v129, vcc, 0, v65, vcc
	s_waitcnt vmcnt(5)
	v_add_co_u32_e32 v140, vcc, 0x30000, v66
	global_load_dwordx4 v[136:139], v[128:129], off
	s_nop 0
	v_addc_co_u32_e32 v141, vcc, 0, v67, vcc
	global_load_dwordx4 v[128:131], v[66:67], off
	s_nop 0
	global_load_dwordx4 v[140:143], v[140:141], off
	v_mov_b64_e32 v[148:149], v[64:65]
	v_mov_b64_e32 v[150:151], v[66:67]

; DI void attn_diff_unit(const Params& p, int li, int b, int h, int qb, char* smem, bool pre, int nh, bool has_next) {
;     ...
;     if (kt + 1 < 32) put_stage(smem + ((kt + 1) & 1) * STG);
;     ...
;     if (kt + 2 < 32) get_stage(kt + 2);
.LBB0_590:
	s_andn2_b64 vcc, exec, s[2:3]
	s_cbranch_vccnz .LBB0_592
	v_readfirstlane_b32 s100, v148
	v_readfirstlane_b32 s101, v149
	s_nop 3
	s_add_u32 s100, s100, s34
	s_addc_u32 s101, s101, s35
	s_add_u32 s100, s100, 0xfffd0000
	s_addc_u32 s101, s101, -1
	s_add_u32 vcc_lo, s100, 0x4000000
	s_addc_u32 vcc_hi, s101, 0
	global_load_dwordx4 v[112:115], v247, s[100:101]
	global_load_dwordx4 v[120:123], v247, vcc
	global_load_dwordx4 v[124:127], v248, s[100:101]
	global_load_dwordx4 v[132:135], v248, vcc
	global_load_dwordx4 v[116:119], v246, s[100:101]
	global_load_dwordx4 v[136:139], v249, s[100:101]
	global_load_dwordx4 v[128:131], v246, vcc
	global_load_dwordx4 v[140:143], v249, vcc
.LBB0_592:
	s_addk_i32 s24, 0x80
	s_add_u32 s34, s34, 0x40000
	s_addc_u32 s35, s35, 0
	s_cmpk_eq_i32 s24, 0x1000
	s_cbranch_scc1 .LBB0_594
	s_mov_b32 s43, s44
	s_xor_b32 s45, s45, 0x12800
	s_branch .LBB0_568

; DI f32x16 mfma32(bf16x8 a, bf16x8 b, f32x16 c) { return __builtin_amdgcn_mfma_f32_32x32x16_bf16(a, b, c, 0, 0, 0); }
; DI bool softmax_tile(f32x16& s0, f32x16& s1, float& m, float& l, float& alpha, bf16x8* pf, int lane, bool first, bool check) {
;     ...
;   float sum = 0.f;
; #pragma unroll
;   for (int i = 0; i < 16; ++i) { s0[i] = __builtin_amdgcn_exp2f(s0[i]); sum += s0[i]; }
; #pragma unroll
;   for (int i = 0; i < 16; ++i) { s1[i] = __builtin_amdgcn_exp2f(s1[i]); sum += s1[i]; }
;   l += sum;
; DI void attn_mla_unit(const Params& p, int b, int h, int qb, char* smem, bool pre, int nh, bool has_next) {
;     ...
;       f32x16 s0, s1;
; #pragma unroll
;       for (int i = 0; i < 16; ++i) { s0[i] = -m; s1[i] = -m; }
;       {
;         bf16x8 kf[12];
; #pragma unroll
;         for (int s = 0; s < 6; ++s) {
;           kf[2 * s] = *(const bf16x8*)(ks + (sub * 64 + r32) * KR + (s * 16 + hh * 8) * 2);
;           kf[2 * s + 1] = *(const bf16x8*)(ks + (sub * 64 + 32 + r32) * KR + (s * 16 + hh * 8) * 2);
;         }
;         __builtin_amdgcn_sched_barrier(0); __builtin_amdgcn_s_setprio(1);
; #pragma unroll
;         for (int s = 0; s < 6; ++s) { s0 = mfma32(kf[2 * s], qf[s], s0); s1 = mfma32(kf[2 * s + 1], qf[s], s1); }
;       __builtin_amdgcn_s_setprio(0);
; }
;       float alpha; bf16x8 pf[4];
;       const bool resc = softmax_tile(s0, s1, m, l, alpha, pf, lane, (kt == 0) && (sub == 0), (sub == 0) && ((kt & 3) == 0));
.LBB0_1482:
	s_add_i32 s19, s18, -1
	s_bitcmp1_b32 s19, 0
	s_cselect_b32 s16, 0xc800, 0
	s_add_i32 s20, s16, 0
	v_add_u32_e32 v44, s20, v149
	v_add_u32_e32 v67, v44, v144
	ds_read_b128 v[68:71], v67
	ds_read_b128 v[72:75], v67 offset:32
	ds_read_b128 v[76:79], v67 offset:6656
	ds_read_b128 v[132:135], v67 offset:6688
	ds_read_b128 v[154:157], v67 offset:64
	ds_read_b128 v[158:161], v67 offset:96
	ds_read_b128 v[162:165], v67 offset:6720
	ds_read_b128 v[166:169], v67 offset:6752
	ds_read_b128 v[170:173], v67 offset:128
	ds_read_b128 v[174:177], v67 offset:160
	ds_read_b128 v[178:181], v67 offset:6784
	ds_read_b128 v[196:199], v67 offset:6816
	v_xor_b32_e32 v32, 0x80000000, v150
	v_mov_b32_e32 v33, v32
	v_mov_b32_e32 v34, v32
	v_mov_b32_e32 v35, v32
	v_mov_b32_e32 v36, v32
	v_mov_b32_e32 v37, v32
	v_mov_b32_e32 v38, v32
	v_mov_b32_e32 v39, v32
	v_mov_b32_e32 v40, v32
	v_mov_b32_e32 v41, v32
	v_mov_b32_e32 v42, v32
	v_mov_b32_e32 v43, v32
	v_mov_b32_e32 v44, v32
	v_mov_b32_e32 v45, v32
	v_mov_b32_e32 v46, v32
	v_mov_b32_e32 v47, v32
	s_and_b32 s16, s19, 3
	s_setprio 1
	s_waitcnt lgkmcnt(8)
	v_mfma_f32_32x32x16_bf16 v[48:63], v[68:71], v[100:103], v[32:47]
	v_mfma_f32_32x32x16_bf16 v[32:47], v[76:79], v[100:103], v[32:47]
	v_mfma_f32_32x32x16_bf16 v[48:63], v[72:75], v[96:99], v[48:63]
	v_mfma_f32_32x32x16_bf16 v[32:47], v[132:135], v[96:99], v[32:47]
	s_waitcnt lgkmcnt(4)
	v_mfma_f32_32x32x16_bf16 v[48:63], v[154:157], v[92:95], v[48:63]
	v_mfma_f32_32x32x16_bf16 v[32:47], v[162:165], v[92:95], v[32:47]
	v_mfma_f32_32x32x16_bf16 v[48:63], v[158:161], v[88:91], v[48:63]
	v_mfma_f32_32x32x16_bf16 v[32:47], v[166:169], v[88:91], v[32:47]
	s_waitcnt lgkmcnt(0)
	v_mfma_f32_32x32x16_bf16 v[48:63], v[170:173], v[84:87], v[48:63]
	v_mfma_f32_32x32x16_bf16 v[32:47], v[178:181], v[84:87], v[32:47]
	v_mfma_f32_32x32x16_bf16 v[48:63], v[174:177], v[80:83], v[48:63]
	v_mfma_f32_32x32x16_bf16 v[32:47], v[196:199], v[80:83], v[32:47]
	s_setprio 0
	s_nop 9
	v_exp_f32_e32 v48, v48
	v_exp_f32_e32 v49, v49
	v_exp_f32_e32 v50, v50
	v_exp_f32_e32 v51, v51
	v_add_f32_e32 v66, 0, v48
	v_exp_f32_e32 v52, v52
	v_add_f32_e32 v66, v49, v66
	v_exp_f32_e32 v53, v53
	v_add_f32_e32 v66, v50, v66
	v_exp_f32_e32 v54, v54
	v_add_f32_e32 v66, v51, v66
	v_exp_f32_e32 v55, v55
	v_add_f32_e32 v66, v52, v66
	v_exp_f32_e32 v56, v56
	v_add_f32_e32 v66, v53, v66
	v_exp_f32_e32 v57, v57
	v_add_f32_e32 v66, v54, v66
	v_exp_f32_e32 v58, v58
	v_add_f32_e32 v66, v55, v66
	v_exp_f32_e32 v59, v59
	v_add_f32_e32 v66, v56, v66
	v_exp_f32_e32 v60, v60
	v_add_f32_e32 v66, v57, v66
	v_exp_f32_e32 v61, v61
	v_add_f32_e32 v66, v58, v66
	v_exp_f32_e32 v62, v62
	v_add_f32_e32 v66, v59, v66
	v_exp_f32_e32 v63, v63
	v_add_f32_e32 v66, v60, v66
	v_exp_f32_e32 v68, v32
	v_add_f32_e32 v66, v61, v66
	v_exp_f32_e32 v33, v33
	v_add_f32_e32 v66, v62, v66
	v_exp_f32_e32 v34, v34
	v_add_f32_e32 v66, v63, v66
	v_exp_f32_e32 v35, v35
	v_add_f32_e32 v32, v68, v66
	v_exp_f32_e32 v36, v36
	v_add_f32_e32 v32, v33, v32
	v_exp_f32_e32 v37, v37
	v_add_f32_e32 v32, v34, v32
	v_exp_f32_e32 v38, v38
	v_add_f32_e32 v32, v35, v32
	v_exp_f32_e32 v39, v39
	v_add_f32_e32 v32, v36, v32
	v_exp_f32_e32 v40, v40
	v_add_f32_e32 v32, v37, v32
	v_exp_f32_e32 v41, v41
	v_add_f32_e32 v32, v38, v32
	v_exp_f32_e32 v42, v42
	v_add_f32_e32 v32, v39, v32
	v_exp_f32_e32 v43, v43
	v_add_f32_e32 v32, v40, v32
	v_exp_f32_e32 v44, v44
	v_add_f32_e32 v32, v41, v32
	v_exp_f32_e32 v45, v45
	v_add_f32_e32 v32, v42, v32
	v_exp_f32_e32 v46, v46
	v_add_f32_e32 v32, v43, v32
	v_exp_f32_e32 v47, v47
	v_add_f32_e32 v32, v44, v32
	v_add_f32_e32 v32, v45, v32
	v_add_f32_e32 v32, v46, v32
	v_add_f32_e32 v32, v47, v32
	s_cmp_lg_u32 s16, 0
	v_add_f32_e32 v66, v153, v32
	s_cbranch_scc0 .LBB0_1484
	s_mov_b64 s[16:17], 0
	v_mov_b32_e32 v32, 1.0
	s_branch .LBB0_1487

; DI f32x16 mfma32(bf16x8 a, bf16x8 b, f32x16 c) { return __builtin_amdgcn_mfma_f32_32x32x16_bf16(a, b, c, 0, 0, 0); }
; DI void attn_mla_unit(const Params& p, int b, int h, int qb, char* smem, bool pre, int nh, bool has_next) {
;     ...
;       {
;         bf16x8 vf[8];
; #pragma unroll
;         for (int s = 0; s < 4; ++s) { vf[2 * s] = ld_vfrag_tr(vs, vbase, VR, sub * 64 + 16 * s, 0); vf[2 * s + 1] = ld_vfrag_tr(vs, vbase, VR, sub * 64 + 16 * s, 32); }
;         __builtin_amdgcn_sched_barrier(0); __builtin_amdgcn_s_setprio(1);
; #pragma unroll
;         for (int s = 0; s < 4; ++s) { O0 = mfma32(vf[2 * s], pf[s], O0); O1 = mfma32(vf[2 * s + 1], pf[s], O1); }
;       __builtin_amdgcn_s_setprio(0);
; }
;       if (resc) { scale16(O0, alpha); scale16(O1, alpha); }
.LBB0_1487:
	v_add_u32_e32 v69, s20, v148
	v_cvt_pk_bf16_f32 v48, v48, v49
	v_cvt_pk_bf16_f32 v49, v50, v51
	v_cvt_pk_bf16_f32 v50, v52, v53
	v_cvt_pk_bf16_f32 v52, v56, v57
	v_cvt_pk_bf16_f32 v56, v68, v33
	v_add_u32_e32 v68, v69, v147
	v_cvt_pk_bf16_f32 v51, v54, v55
	v_cvt_pk_bf16_f32 v53, v58, v59
	v_cvt_pk_bf16_f32 v54, v60, v61
	v_cvt_pk_bf16_f32 v55, v62, v63
	v_cvt_pk_bf16_f32 v57, v34, v35
	v_cvt_pk_bf16_f32 v58, v36, v37
	v_cvt_pk_bf16_f32 v59, v38, v39
	v_cvt_pk_bf16_f32 v34, v40, v41
	v_cvt_pk_bf16_f32 v35, v42, v43
	v_cvt_pk_bf16_f32 v36, v44, v45
	ds_read_b64_tr_b16 v[38:39], v68 offset:26624
	ds_read_b64_tr_b16 v[40:41], v68 offset:28160
	ds_read_b64_tr_b16 v[42:43], v68 offset:26688
	ds_read_b64_tr_b16 v[44:45], v68 offset:28224
	ds_read_b64_tr_b16 v[60:61], v68 offset:29696
	ds_read_b64_tr_b16 v[62:63], v68 offset:31232
	ds_read_b64_tr_b16 v[70:71], v68 offset:29760
	ds_read_b64_tr_b16 v[72:73], v68 offset:31296
	ds_read_b64_tr_b16 v[74:75], v68 offset:32768
	ds_read_b64_tr_b16 v[76:77], v68 offset:34304
	ds_read_b64_tr_b16 v[132:133], v68 offset:32832
	ds_read_b64_tr_b16 v[134:135], v68 offset:34368
	ds_read_b64_tr_b16 v[154:155], v68 offset:35840
	ds_read_b64_tr_b16 v[156:157], v68 offset:37376
	ds_read_b64_tr_b16 v[158:159], v68 offset:35904
	ds_read_b64_tr_b16 v[160:161], v68 offset:37440
	v_cvt_pk_bf16_f32 v37, v46, v47
	s_setprio 1
	s_waitcnt lgkmcnt(8)
	v_mfma_f32_32x32x16_bf16 v[16:31], v[38:41], v[48:51], v[16:31]
	v_mfma_f32_32x32x16_bf16 v[0:15], v[42:45], v[48:51], v[0:15]
	v_mfma_f32_32x32x16_bf16 v[16:31], v[60:63], v[52:55], v[16:31]
	v_mfma_f32_32x32x16_bf16 v[0:15], v[70:73], v[52:55], v[0:15]
	s_waitcnt lgkmcnt(0)
	v_mfma_f32_32x32x16_bf16 v[16:31], v[74:77], v[56:59], v[16:31]
	v_mfma_f32_32x32x16_bf16 v[0:15], v[132:135], v[56:59], v[0:15]
	v_mfma_f32_32x32x16_bf16 v[16:31], v[154:157], v[34:37], v[16:31]
	v_mfma_f32_32x32x16_bf16 v[0:15], v[158:161], v[34:37], v[0:15]
	s_setprio 0
	s_andn2_b64 vcc, exec, s[16:17]
	s_cbranch_vccnz .LBB0_1489
	s_nop 7
	v_pk_mul_f32 v[30:31], v[32:33], v[30:31] op_sel_hi:[0,1]
	v_pk_mul_f32 v[28:29], v[32:33], v[28:29] op_sel_hi:[0,1]
	v_pk_mul_f32 v[26:27], v[32:33], v[26:27] op_sel_hi:[0,1]
	v_pk_mul_f32 v[24:25], v[32:33], v[24:25] op_sel_hi:[0,1]
	v_pk_mul_f32 v[22:23], v[32:33], v[22:23] op_sel_hi:[0,1]
	v_pk_mul_f32 v[20:21], v[32:33], v[20:21] op_sel_hi:[0,1]
	v_pk_mul_f32 v[18:19], v[32:33], v[18:19] op_sel_hi:[0,1]
	v_pk_mul_f32 v[16:17], v[32:33], v[16:17] op_sel_hi:[0,1]
	v_pk_mul_f32 v[14:15], v[32:33], v[14:15] op_sel_hi:[0,1]
	v_pk_mul_f32 v[12:13], v[32:33], v[12:13] op_sel_hi:[0,1]
	v_pk_mul_f32 v[10:11], v[32:33], v[10:11] op_sel_hi:[0,1]
	v_pk_mul_f32 v[8:9], v[32:33], v[8:9] op_sel_hi:[0,1]
	v_pk_mul_f32 v[6:7], v[32:33], v[6:7] op_sel_hi:[0,1]
	v_pk_mul_f32 v[4:5], v[32:33], v[4:5] op_sel_hi:[0,1]
	v_pk_mul_f32 v[2:3], v[32:33], v[2:3] op_sel_hi:[0,1]
	v_pk_mul_f32 v[0:1], v[32:33], v[0:1] op_sel_hi:[0,1]
; DI f32x16 mfma32(bf16x8 a, bf16x8 b, f32x16 c) { return __builtin_amdgcn_mfma_f32_32x32x16_bf16(a, b, c, 0, 0, 0); }
; DI void attn_mla_unit(const Params& p, int b, int h, int qb, char* smem, bool pre, int nh, bool has_next) {
;     ...
;       f32x16 s0, s1;
; #pragma unroll
;       for (int i = 0; i < 16; ++i) { s0[i] = -m; s1[i] = -m; }
;       {
;         bf16x8 kf[12];
; #pragma unroll
;         for (int s = 0; s < 6; ++s) {
;           kf[2 * s] = *(const bf16x8*)(ks + (sub * 64 + r32) * KR + (s * 16 + hh * 8) * 2);
;           kf[2 * s + 1] = *(const bf16x8*)(ks + (sub * 64 + 32 + r32) * KR + (s * 16 + hh * 8) * 2);
;         }
;         __builtin_amdgcn_sched_barrier(0); __builtin_amdgcn_s_setprio(1);
; #pragma unroll
;         for (int s = 0; s < 6; ++s) { s0 = mfma32(kf[2 * s], qf[s], s0); s1 = mfma32(kf[2 * s + 1], qf[s], s1); }
;       __builtin_amdgcn_s_setprio(0);
; }
;       float alpha; bf16x8 pf[4];
;       const bool resc = softmax_tile(s0, s1, m, l, alpha, pf, lane, (kt == 0) && (sub == 0), (sub == 0) && ((kt & 3) == 0));
;       {
;         bf16x8 vf[8];
; #pragma unroll
;         for (int s = 0; s < 4; ++s) { vf[2 * s] = ld_vfrag_tr(vs, vbase, VR, sub * 64 + 16 * s, 0); vf[2 * s + 1] = ld_vfrag_tr(vs, vbase, VR, sub * 64 + 16 * s, 32); }
;         __builtin_amdgcn_sched_barrier(0); __builtin_amdgcn_s_setprio(1);
; #pragma unroll
;         for (int s = 0; s < 4; ++s) { O0 = mfma32(vf[2 * s], pf[s], O0); O1 = mfma32(vf[2 * s + 1], pf[s], O1); }
;       __builtin_amdgcn_s_setprio(0);
; }
;       if (resc) { scale16(O0, alpha); scale16(O1, alpha); }
;     }
;     if (kt + 1 < 32) put_stage(smem + ((kt + 1) & 1) * STG);
;     else if (has_next) put_stage(smem);
;     __syncthreads();
;     if (kt + 2 < 32) get_stage(kt + 2);
;     else if (kt == 30 && has_next) { gk += (nh - h) * 64; gv += (nh - h) * 64; get_stage(0); }
.LBB0_1489:
	ds_read_b128 v[70:73], v67 offset:13312
	ds_read_b128 v[74:77], v67 offset:13344
	ds_read_b128 v[132:135], v67 offset:19968
	ds_read_b128 v[154:157], v67 offset:20000
	ds_read_b128 v[158:161], v67 offset:13376
	ds_read_b128 v[162:165], v67 offset:13408
	ds_read_b128 v[166:169], v67 offset:20032
	ds_read_b128 v[170:173], v67 offset:20064
	ds_read_b128 v[174:177], v67 offset:13440
	ds_read_b128 v[178:181], v67 offset:13472
	ds_read_b128 v[196:199], v67 offset:20096
	ds_read_b128 v[200:203], v67 offset:20128
	v_xor_b32_e32 v32, 0x80000000, v150
	v_mov_b32_e32 v33, v32
	v_mov_b32_e32 v34, v32
	v_mov_b32_e32 v35, v32
	v_mov_b32_e32 v36, v32
	v_mov_b32_e32 v37, v32
	v_mov_b32_e32 v38, v32
	v_mov_b32_e32 v39, v32
	v_mov_b32_e32 v40, v32
	v_mov_b32_e32 v41, v32
	v_mov_b32_e32 v42, v32
	v_mov_b32_e32 v43, v32
	v_mov_b32_e32 v44, v32
	v_mov_b32_e32 v45, v32
	v_mov_b32_e32 v46, v32
	v_mov_b32_e32 v47, v32
	s_setprio 1
	s_waitcnt lgkmcnt(8)
	v_mfma_f32_32x32x16_bf16 v[48:63], v[70:73], v[100:103], v[32:47]
	v_mfma_f32_32x32x16_bf16 v[32:47], v[132:135], v[100:103], v[32:47]
	v_mfma_f32_32x32x16_bf16 v[48:63], v[74:77], v[96:99], v[48:63]
	v_mfma_f32_32x32x16_bf16 v[32:47], v[154:157], v[96:99], v[32:47]
	s_waitcnt lgkmcnt(4)
	v_mfma_f32_32x32x16_bf16 v[48:63], v[158:161], v[92:95], v[48:63]
	v_mfma_f32_32x32x16_bf16 v[32:47], v[166:169], v[92:95], v[32:47]
	v_mfma_f32_32x32x16_bf16 v[48:63], v[162:165], v[88:91], v[48:63]
	v_mfma_f32_32x32x16_bf16 v[32:47], v[170:173], v[88:91], v[32:47]
	s_waitcnt lgkmcnt(0)
	v_mfma_f32_32x32x16_bf16 v[48:63], v[174:177], v[84:87], v[48:63]
	v_mfma_f32_32x32x16_bf16 v[32:47], v[196:199], v[84:87], v[32:47]
	v_mfma_f32_32x32x16_bf16 v[48:63], v[178:181], v[80:83], v[48:63]
	v_mfma_f32_32x32x16_bf16 v[32:47], v[200:203], v[80:83], v[32:47]
	s_setprio 0
	ds_read_b64_tr_b16 v[132:133], v68 offset:38912
	ds_read_b64_tr_b16 v[134:135], v68 offset:40448
	ds_read_b64_tr_b16 v[156:157], v68 offset:40512
	ds_read_b64_tr_b16 v[154:155], v68 offset:38976
	ds_read_b64_tr_b16 v[158:159], v68 offset:41984
	ds_read_b64_tr_b16 v[160:161], v68 offset:43520
	ds_read_b64_tr_b16 v[164:165], v68 offset:43584
	ds_read_b64_tr_b16 v[162:163], v68 offset:42048
	ds_read_b64_tr_b16 v[166:167], v68 offset:45056
	ds_read_b64_tr_b16 v[168:169], v68 offset:46592
	ds_read_b64_tr_b16 v[172:173], v68 offset:46656
	ds_read_b64_tr_b16 v[170:171], v68 offset:45120
	ds_read_b64_tr_b16 v[174:175], v68 offset:48128
	ds_read_b64_tr_b16 v[176:177], v68 offset:49664
	ds_read_b64_tr_b16 v[180:181], v68 offset:49728
	ds_read_b64_tr_b16 v[178:179], v68 offset:48192
	v_exp_f32_e32 v40, v40
	v_exp_f32_e32 v41, v41
	v_exp_f32_e32 v42, v42
	v_exp_f32_e32 v43, v43
	v_exp_f32_e32 v44, v44
	v_exp_f32_e32 v45, v45
	v_exp_f32_e32 v46, v46
	v_exp_f32_e32 v47, v47
	v_exp_f32_e32 v48, v48
	v_exp_f32_e32 v49, v49
	v_exp_f32_e32 v50, v50
	v_exp_f32_e32 v51, v51
	v_exp_f32_e32 v52, v52
	v_exp_f32_e32 v53, v53
	v_exp_f32_e32 v54, v54
	v_exp_f32_e32 v55, v55
	v_exp_f32_e32 v56, v56
	v_exp_f32_e32 v57, v57
	v_exp_f32_e32 v58, v58
	v_exp_f32_e32 v59, v59
	v_exp_f32_e32 v60, v60
	v_exp_f32_e32 v61, v61
	v_exp_f32_e32 v62, v62
	v_exp_f32_e32 v63, v63
	v_exp_f32_e32 v67, v32
	v_exp_f32_e32 v69, v33
	v_exp_f32_e32 v70, v34
	v_exp_f32_e32 v71, v35
	v_exp_f32_e32 v36, v36
	v_exp_f32_e32 v37, v37
	v_exp_f32_e32 v38, v38
	v_exp_f32_e32 v39, v39
	v_cvt_pk_bf16_f32 v32, v40, v41
	v_cvt_pk_bf16_f32 v33, v42, v43
	v_cvt_pk_bf16_f32 v34, v44, v45
	v_cvt_pk_bf16_f32 v35, v46, v47
	v_cvt_pk_bf16_f32 v72, v67, v69
	v_cvt_pk_bf16_f32 v73, v70, v71
	v_cvt_pk_bf16_f32 v74, v36, v37
	v_cvt_pk_bf16_f32 v75, v38, v39
	v_cvt_pk_bf16_f32 v76, v56, v57
	v_cvt_pk_bf16_f32 v77, v58, v59
	v_cvt_pk_bf16_f32 v78, v60, v61
	v_cvt_pk_bf16_f32 v79, v62, v63
	v_cvt_pk_bf16_f32 v196, v48, v49
	v_cvt_pk_bf16_f32 v197, v50, v51
	v_cvt_pk_bf16_f32 v198, v52, v53
	v_cvt_pk_bf16_f32 v199, v54, v55
	s_setprio 1
	s_waitcnt lgkmcnt(8)
	v_mfma_f32_32x32x16_bf16 v[16:31], v[132:135], v[196:199], v[16:31]
	v_mfma_f32_32x32x16_bf16 v[0:15], v[154:157], v[196:199], v[0:15]
	v_mfma_f32_32x32x16_bf16 v[16:31], v[158:161], v[76:79], v[16:31]
	v_mfma_f32_32x32x16_bf16 v[0:15], v[162:165], v[76:79], v[0:15]
	s_waitcnt lgkmcnt(0)
	v_mfma_f32_32x32x16_bf16 v[16:31], v[166:169], v[72:75], v[16:31]
	v_mfma_f32_32x32x16_bf16 v[0:15], v[170:173], v[72:75], v[0:15]
	v_mfma_f32_32x32x16_bf16 v[16:31], v[174:177], v[32:35], v[16:31]
	v_mfma_f32_32x32x16_bf16 v[0:15], v[178:181], v[32:35], v[0:15]
	s_setprio 0
	s_bitcmp1_b32 s18, 0
	s_cselect_b32 s16, 0xc800, 0
	s_add_i32 s16, s16, 0
	v_add3_u32 v32, s16, v142, v138
	v_add3_u32 v33, s16, v139, v138
	s_waitcnt vmcnt(4)
	ds_write_b128 v32, v[104:107]
	s_waitcnt vmcnt(2)
	ds_write_b128 v33, v[108:111] offset:26624
	s_waitcnt vmcnt(2)
	ds_write_b128 v32, v[112:115] offset:13312
	s_waitcnt vmcnt(1)
	ds_write_b128 v33, v[116:119] offset:38912
	v_add3_u32 v32, s16, v143, v146
	s_cmp_gt_u32 s19, 29
	s_mov_b64 s[16:17], -1
	s_waitcnt vmcnt(0)
	ds_write_b128 v32, v[120:123] offset:128
	s_waitcnt lgkmcnt(0)
	s_barrier
	s_cbranch_scc0 .LBB0_1493
	s_cmp_lg_u32 s12, 0x410000
	s_cselect_b64 s[16:17], -1, 0
	s_xor_b64 s[20:21], s[10:11], -1
	s_or_b64 s[16:17], s[20:21], s[16:17]
	s_and_b64 vcc, exec, s[16:17]
	v_mov_b64_e32 v[32:33], v[128:129]
	v_mov_b64_e32 v[34:35], v[130:131]
	s_cbranch_vccnz .LBB0_1492
	v_lshl_add_u64 v[32:33], v[128:129], 0, s[14:15]
	v_add_co_u32_e32 v72, vcc, 0x10000, v32
	v_lshl_add_u64 v[34:35], v[130:131], 0, s[14:15]
	s_nop 0
	v_addc_co_u32_e32 v73, vcc, 0, v33, vcc
	global_load_dwordx4 v[104:107], v[32:33], off
	global_load_dwordx4 v[112:115], v[72:73], off
	v_add_co_u32_e32 v72, vcc, 0x10000, v34
	s_nop 1
	v_addc_co_u32_e32 v73, vcc, 0, v35, vcc
	global_load_dwordx4 v[108:111], v[34:35], off
	global_load_dwordx4 v[116:119], v[72:73], off
	global_load_dwordx4 v[120:123], v[126:127], off
